# attention K tile in LDS: XOR-swizzled 16-byte chunks (rows 4..11 mod 16), K-fragment ds_read_b128 now bank-conflict-free (LDS bank conflicts lever); on top of v85
# speedup vs baseline: 1.0081x; 1.0081x over previous
; #define LAS __attribute__((address_space(3)))
; __device__ __forceinline__ void phase_attn(const Params& p, LAS unsigned char* lds) {
;     const int tid = threadIdx.x, lane = tid & 63, wave = __builtin_amdgcn_readfirstlane(tid >> 6), g = lane >> 4, lc = lane & 15;
;     const bf16_t* Q = (const bf16_t*)(p.ws + WS_F); const bf16_t* KN = (const bf16_t*)(p.ws + WS_XL); const bf16_t* V = KN + (size_t)T * NKV;
;     const bf16_t* KR = (const bf16_t*)(p.ws + WS_KR); bf16_t* O = (bf16_t*)(p.ws + WS_ZQ);
;     const float csc = 0.10206207261596577f * 1.4426950408889634f;
;     const int srow = tid >> 3, sch = tid & 7;
;     const int rrow = (tid & 255) >> 2, rch = tid & 3;
;     const int vtr = (4 * g + (lc >> 2)) * AV_PITCH + (4 * (lc & 3)) * 2;
;     ...
;         gk = *(const u32x4*)(KN + (size_t)(row0 + srow) * NKV + 64 * h + 8 * sch);
;         gv = *(const u32x4*)(V + (size_t)(row0 + srow) * NKV + 64 * h + 8 * sch);
;         gr = *(const u32x4*)(KR + (size_t)(row0 + rrow) * 32 + 8 * rch);
;         __syncthreads();
;         *(LAS u32x4*)(lds + srow * AK_PITCH + sch * 16) = gk;
;         *(LAS u32x4*)(lds + AK_BYTES + srow * AV_PITCH + sch * 16) = gv;
;         if (tid < 256) *(LAS u32x4*)(lds + rrow * AK_PITCH + 128 + rch * 16) = gr;
.LBB0_726:
	v_bfe_u32 v2, v128, 4, 2
	v_bfe_u32 v0, v128, 2, 2
	v_lshl_or_b32 v0, v2, 2, v0
	v_mul_u32_u24_e32 v0, 0xa0, v0
	v_lshlrev_b32_e32 v1, 3, v128
	s_waitcnt vmcnt(0)
	v_mov_b32_e32 v81, 0
	v_and_or_b32 v9, v1, 24, v0
	v_lshlrev_b32_e32 v0, 4, v2
	v_mov_b32_e32 v1, v81
	v_lshl_add_u64 v[82:83], s[18:19], 0, v[0:1]
	v_mbcnt_lo_u32_b32 v1, -1, 0
	v_mbcnt_hi_u32_b32 v1, -1, v1
	v_and_b32_e32 v6, 64, v1
	s_add_u32 s8, s92, 0x28000000
	v_xor_b32_e32 v5, 32, v1
	v_add_u32_e32 v10, 64, v6
	s_addc_u32 s9, s93, 0
	v_and_b32_e32 v8, 7, v128
	s_lshr_b32 s0, s0, 1
	v_cmp_lt_i32_e32 vcc, v5, v10
	v_and_b32_e32 v4, 3, v128
	s_and_b32 s10, s0, 0x7fffffe0
	v_lshlrev_b32_e32 v80, 3, v2
	v_cndmask_b32_e32 v5, v1, v5, vcc
	v_cmp_gt_u32_e64 s[0:1], 2, v2
	v_lshlrev_b32_e32 v2, 3, v8
	v_lshlrev_b32_e32 v86, 4, v8
	v_add_u32_e32 v8, 0, v0
	v_xor_b32_e32 v0, 16, v1
	v_lshrrev_b32_e32 v169, 3, v128
	v_lshlrev_b32_e32 v171, 2, v5
	v_lshlrev_b32_e32 v4, 4, v4
	v_mov_b32_e32 v5, v81
	s_movk_i32 s12, 0xd0
	v_cmp_lt_i32_e32 vcc, v0, v10
	v_lshl_add_u64 v[6:7], s[92:93], 0, v[4:5]
	s_mov_b64 s[4:5], 0x3400000
	v_mad_u32_u24 v5, v169, s12, 0
	s_movk_i32 s13, 0xffd0
	v_cndmask_b32_e32 v0, v1, v0, vcc
	v_lshl_add_u64 v[84:85], v[6:7], 0, s[4:5]
	v_mad_i32_i24 v6, v169, s13, v5
	v_lshlrev_b32_e32 v172, 2, v0
	v_mov_b32_e32 v87, v81
	v_lshlrev_b32_e32 v0, 1, v128
	v_and_b32_e32 v3, 15, v128
	v_bfe_u32 v170, v128, 2, 6
	v_lshl_add_u64 v[88:89], s[24:25], 0, v[86:87]
	v_lshl_add_u64 v[90:91], s[8:9], 0, v[86:87]
	v_mad_u32_u24 v87, v169, 48, v6
	v_lshl_add_u64 v[92:93], s[16:17], 0, v[80:81]
	v_and_b32_e32 v80, 32, v0
	s_movk_i32 s4, 0x100
	v_mad_u32_u24 v7, v170, s12, 0
	v_mad_i32_i24 v10, v169, s13, v87
	v_mul_u32_u24_e32 v11, 0xd0, v3
	v_lshl_add_u64 v[0:1], s[92:93], 0, v[80:81]
	s_mov_b64 s[12:13], 0x32c0000
	v_lshlrev_b32_e32 v96, 1, v2
	s_mov_b32 s11, 0
	v_cmp_gt_u32_e64 s[4:5], s4, v128
	v_or_b32_e32 v173, s10, v3
	v_lshl_add_u64 v[94:95], v[0:1], 0, s[12:13]
	s_movk_i32 s33, 0xf000
	s_mov_b32 s34, 0x8000
	s_movk_i32 s35, 0x600
	v_mov_b32_e32 v174, 0xfef
	v_mov_b32_e32 v175, 0x7ef
	s_mov_b64 s[12:13], 0x40000
	s_waitcnt lgkmcnt(0)
	s_mov_b32 s36, 0x40000
	v_mov_b32_e32 v176, 0xfff
	v_mov_b32_e32 v177, 0x7ff
	v_mov_b32_e32 v98, v96
	v_mov_b32_e32 v99, v81
	v_add_u32_e32 v240, 4, v169
	v_and_b32_e32 v240, 8, v240
	v_lshlrev_b32_e32 v240, 1, v240
	v_xor_b32_e32 v240, v86, v240
	v_add_u32_e32 v178, v5, v240
	v_add_u32_e32 v179, v6, v86
	s_mov_b32 s37, 0x3e16c740
	v_add_u32_e32 v180, v10, v86
	v_add_u32_e32 v240, 4, v170
	v_and_b32_e32 v240, 8, v240
	v_lshlrev_b32_e32 v240, 1, v240
	v_xor_b32_e32 v240, v4, v240
	v_add_u32_e32 v181, v7, v240
	v_add_u32_e32 v240, 4, v3
	v_and_b32_e32 v240, 8, v240
	v_lshlrev_b32_e32 v240, 1, v240
	v_xor_b32_e32 v240, v8, v240
	v_add_u32_e32 v182, v11, v240
	v_add_u32_e32 v183, 0, v9
	s_branch .LBB0_728

.LBB0_732:
	ds_read_b128 v[110:113], v182
	ds_read_b128 v[122:125], v182 offset:64
	ds_read_b128 v[118:121], v182 offset:3328
	ds_read_b128 v[136:139], v182 offset:128
	ds_read_b128 v[140:143], v182 offset:6656
	ds_read_b128 v[148:151], v182 offset:6720
	ds_read_b128 v[152:155], v182 offset:9984
	ds_read_b128 v[156:159], v182 offset:6784
	s_waitcnt lgkmcnt(7)
	v_mfma_f32_16x16x32_bf16 v[114:117], v[110:113], v[0:3], 0
	ds_read_b128 v[164:167], v182 offset:3392
	ds_read_b128 v[186:189], v182 offset:3456
	ds_read_b128 v[190:193], v182 offset:10048
	ds_read_b128 v[194:197], v182 offset:10112
	s_add_i32 s28, s31, -3
	s_waitcnt lgkmcnt(9)
	v_mfma_f32_16x16x32_bf16 v[130:133], v[118:121], v[0:3], 0
	s_cmp_ge_u32 s28, s30
	v_mfma_f32_16x16x32_bf16 v[114:117], v[122:125], v[4:7], v[114:117]
	s_waitcnt lgkmcnt(7)
	v_mfma_f32_16x16x32_bf16 v[144:147], v[140:143], v[0:3], 0
	s_waitcnt lgkmcnt(5)
	v_mfma_f32_16x16x32_bf16 v[160:163], v[152:155], v[0:3], 0
	s_waitcnt lgkmcnt(3)
	v_mfma_f32_16x16x32_bf16 v[130:133], v[164:167], v[4:7], v[130:133]
	v_mfma_f32_16x16x32_bf16 v[114:117], v[136:139], v[16:19], v[114:117]
	v_mfma_f32_16x16x32_bf16 v[144:147], v[148:151], v[4:7], v[144:147]
	s_waitcnt lgkmcnt(1)
	v_mfma_f32_16x16x32_bf16 v[160:163], v[190:193], v[4:7], v[160:163]
	s_nop 4
	v_max_f32_e32 v80, v115, v115
	v_max_f32_e32 v126, v114, v114
	v_max_f32_e32 v80, v126, v80
	v_mfma_f32_16x16x32_bf16 v[130:133], v[186:189], v[16:19], v[130:133]
	v_max3_f32 v80, v80, v116, v117
	v_mfma_f32_16x16x32_bf16 v[198:201], v[156:159], v[16:19], v[144:147]
	s_waitcnt lgkmcnt(0)
	v_mfma_f32_16x16x32_bf16 v[160:163], v[194:197], v[16:19], v[160:163]
	s_nop 3
	v_max3_f32 v80, v80, v130, v131
	v_max3_f32 v80, v80, v132, v133
	v_max3_f32 v80, v80, v198, v199
	v_max3_f32 v80, v80, v200, v201
	v_mfma_f32_16x16x32_bf16 v[202:205], v[110:113], v[8:11], 0
	v_max3_f32 v80, v80, v160, v161
	v_max3_f32 v80, v80, v162, v163
	v_mov_b32_e32 v126, v80
	s_nop 1
	v_permlane16_swap_b32 v80, v126
	v_mfma_f32_16x16x32_bf16 v[206:209], v[118:121], v[8:11], 0
	s_waitcnt lgkmcnt(0)
	v_max_f32_e32 v126, v126, v126
	v_max_f32_e32 v80, v80, v126
	v_mov_b32_e32 v126, v80
	s_nop 1
	v_permlane32_swap_b32 v80, v126
	v_mfma_f32_16x16x32_bf16 v[140:143], v[140:143], v[8:11], 0
	s_waitcnt lgkmcnt(0)
	v_max_f32_e32 v126, v126, v126
	v_mfma_f32_16x16x32_bf16 v[152:155], v[152:155], v[8:11], 0
	v_max_f32_e32 v80, v80, v126
	v_mul_f32_e32 v80, 0x3e16c740, v80
	v_max_f32_e32 v126, v184, v184
	v_mfma_f32_16x16x32_bf16 v[202:205], v[122:125], v[12:15], v[202:205]
	v_max_f32_e32 v146, v126, v80
	v_fma_f32 v110, v114, s37, -v146
	v_exp_f32_e32 v111, v110
	v_mfma_f32_16x16x32_bf16 v[164:167], v[164:167], v[12:15], v[206:209]
	v_fma_f32 v110, v115, s37, -v146
	v_exp_f32_e32 v113, v110
	v_fma_f32 v110, v116, s37, -v146
	v_mfma_f32_16x16x32_bf16 v[140:143], v[148:151], v[12:15], v[140:143]
	v_exp_f32_e32 v115, v110
	v_fma_f32 v110, v117, s37, -v146
	v_exp_f32_e32 v117, v110
	v_mfma_f32_16x16x32_bf16 v[148:151], v[190:193], v[12:15], v[152:155]
	v_fma_f32 v110, v130, s37, -v146
	v_exp_f32_e32 v119, v110
	v_fma_f32 v110, v131, s37, -v146
	v_mfma_f32_16x16x32_bf16 v[152:155], v[136:139], v[44:47], v[202:205]
	v_exp_f32_e32 v121, v110
	v_fma_f32 v110, v132, s37, -v146
	v_exp_f32_e32 v123, v110
	v_mfma_f32_16x16x32_bf16 v[164:167], v[186:189], v[44:47], v[164:167]
	v_fma_f32 v110, v133, s37, -v146
	s_nop 2
	v_max_f32_e32 v112, v153, v153
	v_max_f32_e32 v114, v152, v152
	v_max_f32_e32 v112, v114, v112
	v_mfma_f32_16x16x32_bf16 v[156:159], v[156:159], v[44:47], v[140:143]
	v_max3_f32 v112, v112, v154, v155
	v_max3_f32 v112, v112, v164, v165
	v_max3_f32 v112, v112, v166, v167
	v_mfma_f32_16x16x32_bf16 v[148:151], v[194:197], v[44:47], v[148:151]
	v_exp_f32_e32 v127, v110
	s_nop 2
	v_max3_f32 v112, v112, v156, v157
	v_max3_f32 v112, v112, v158, v159
	v_fma_f32 v110, v198, s37, -v146
	v_exp_f32_e32 v125, v110
	v_max3_f32 v112, v112, v148, v149
	v_max3_f32 v112, v112, v150, v151
	v_mov_b32_e32 v114, v112
	s_nop 1
	v_permlane16_swap_b32 v112, v114
	v_fma_f32 v110, v199, s37, -v146
	v_exp_f32_e32 v133, v110
	v_fma_f32 v110, v200, s37, -v146
	v_exp_f32_e32 v131, v110
	s_waitcnt lgkmcnt(0)
	v_max_f32_e32 v114, v114, v114
	v_max_f32_e32 v112, v112, v114
	v_fma_f32 v110, v201, s37, -v146
	v_mov_b32_e32 v114, v112
	s_nop 1
	v_permlane32_swap_b32 v112, v114
	v_exp_f32_e32 v135, v110
	v_fma_f32 v110, v160, s37, -v146
	v_exp_f32_e32 v137, v110
	v_fma_f32 v110, v161, s37, -v146
	v_exp_f32_e32 v139, v110
	v_fma_f32 v110, v162, s37, -v146
	v_exp_f32_e32 v141, v110
	v_fma_f32 v110, v163, s37, -v146
	v_exp_f32_e32 v143, v110
	s_waitcnt lgkmcnt(0)
	v_max_f32_e32 v110, v114, v114
	v_max_f32_e32 v110, v112, v110
	v_mul_f32_e32 v110, 0x3e16c740, v110
	v_max_f32_e32 v112, v97, v97
	v_max_f32_e32 v145, v112, v110
	v_sub_f32_e32 v80, v184, v146
	v_sub_f32_e32 v97, v97, v145
	v_fma_f32 v110, v152, s37, -v145
	v_fma_f32 v112, v153, s37, -v145
	v_fma_f32 v114, v154, s37, -v145
	v_fma_f32 v116, v155, s37, -v145
	v_fma_f32 v118, v164, s37, -v145
	v_fma_f32 v120, v165, s37, -v145
	v_fma_f32 v122, v166, s37, -v145
	v_fma_f32 v124, v167, s37, -v145
	v_exp_f32_e32 v80, v80
	v_exp_f32_e32 v110, v110
	v_exp_f32_e32 v112, v112
	v_exp_f32_e32 v114, v114
	v_exp_f32_e32 v116, v116
	v_exp_f32_e32 v118, v118
	v_exp_f32_e32 v120, v120
	v_exp_f32_e32 v122, v122
	v_exp_f32_e32 v126, v124
	v_fma_f32 v136, v148, s37, -v145
	v_fma_f32 v138, v149, s37, -v145
	v_fma_f32 v140, v150, s37, -v145
	v_fma_f32 v142, v151, s37, -v145
	v_exp_f32_e32 v144, v97
	ds_read_b64_tr_b16 v[150:151], v183 offset:15872
	ds_read_b64_tr_b16 v[148:149], v183 offset:13312
	ds_read_b64_tr_b16 v[160:161], v183 offset:13344
	ds_read_b64_tr_b16 v[164:165], v183 offset:13376
	ds_read_b64_tr_b16 v[184:185], v183 offset:13408
	ds_read_b64_tr_b16 v[162:163], v183 offset:15904
	ds_read_b64_tr_b16 v[166:167], v183 offset:15936
	ds_read_b64_tr_b16 v[186:187], v183 offset:15968
	v_fma_f32 v130, v157, s37, -v145
	v_cvt_pk_bf16_f32 v152, v111, v113
	v_cvt_pk_bf16_f32 v153, v115, v117
	v_cvt_pk_bf16_f32 v154, v119, v121
	v_cvt_pk_bf16_f32 v155, v123, v127
	v_fma_f32 v124, v156, s37, -v145
	v_exp_f32_e32 v132, v130
	v_fma_f32 v130, v158, s37, -v145
	v_fma_f32 v134, v159, s37, -v145
	v_pk_mul_f32 v[78:79], v[78:79], v[80:81] op_sel_hi:[1,0]
	v_pk_mul_f32 v[76:77], v[76:77], v[80:81] op_sel_hi:[1,0]
	v_pk_mul_f32 v[74:75], v[74:75], v[80:81] op_sel_hi:[1,0]
	v_pk_mul_f32 v[70:71], v[70:71], v[144:145] op_sel_hi:[1,0]
	v_pk_mul_f32 v[68:69], v[68:69], v[144:145] op_sel_hi:[1,0]
	v_cvt_pk_bf16_f32 v156, v110, v112
	v_cvt_pk_bf16_f32 v157, v114, v116
	v_cvt_pk_bf16_f32 v158, v118, v120
	v_cvt_pk_bf16_f32 v159, v122, v126
	v_pk_mul_f32 v[72:73], v[72:73], v[80:81] op_sel_hi:[1,0]
	v_pk_mul_f32 v[66:67], v[66:67], v[80:81] op_sel_hi:[1,0]
	v_pk_mul_f32 v[64:65], v[64:65], v[80:81] op_sel_hi:[1,0]
	v_pk_mul_f32 v[62:63], v[62:63], v[80:81] op_sel_hi:[1,0]
	v_pk_mul_f32 v[58:59], v[58:59], v[144:145] op_sel_hi:[1,0]
	v_pk_mul_f32 v[56:57], v[56:57], v[144:145] op_sel_hi:[1,0]
	v_pk_mul_f32 v[60:61], v[60:61], v[80:81] op_sel_hi:[1,0]
	v_pk_mul_f32 v[54:55], v[54:55], v[144:145] op_sel_hi:[1,0]
	v_pk_mul_f32 v[52:53], v[52:53], v[144:145] op_sel_hi:[1,0]
	v_pk_mul_f32 v[50:51], v[50:51], v[144:145] op_sel_hi:[1,0]
	v_pk_mul_f32 v[48:49], v[48:49], v[144:145] op_sel_hi:[1,0]
	v_exp_f32_e32 v124, v124
	v_exp_f32_e32 v130, v130
	v_exp_f32_e32 v134, v134
	v_exp_f32_e32 v136, v136
	v_exp_f32_e32 v138, v138
	v_exp_f32_e32 v140, v140
	v_exp_f32_e32 v142, v142
	s_waitcnt lgkmcnt(6)
	v_mfma_f32_16x16x32_bf16 v[76:79], v[148:151], v[152:155], v[76:79]
	v_mfma_f32_16x16x32_bf16 v[68:71], v[148:151], v[156:159], v[68:71]
	s_waitcnt lgkmcnt(2)
	v_mfma_f32_16x16x32_bf16 v[148:151], v[160:163], v[152:155], v[72:75]
	v_mfma_f32_16x16x32_bf16 v[56:59], v[160:163], v[156:159], v[56:59]
	v_cvt_pk_bf16_f32 v160, v125, v133
	v_cvt_pk_bf16_f32 v161, v131, v135
	v_cvt_pk_bf16_f32 v162, v137, v139
	s_waitcnt lgkmcnt(1)
	v_mfma_f32_16x16x32_bf16 v[64:67], v[164:167], v[152:155], v[64:67]
	v_cvt_pk_bf16_f32 v163, v141, v143
	v_mfma_f32_16x16x32_bf16 v[52:55], v[164:167], v[156:159], v[52:55]
	v_cvt_pk_bf16_f32 v164, v124, v132
	v_cvt_pk_bf16_f32 v165, v130, v134
	v_cvt_pk_bf16_f32 v166, v136, v138
	s_waitcnt lgkmcnt(0)
	v_mfma_f32_16x16x32_bf16 v[152:155], v[184:187], v[152:155], v[60:63]
	s_nop 2
	ds_read_b64_tr_b16 v[60:61], v183 offset:18432
	ds_read_b64_tr_b16 v[62:63], v183 offset:20992
	v_cvt_pk_bf16_f32 v167, v140, v142
	v_mfma_f32_16x16x32_bf16 v[156:159], v[184:187], v[156:159], v[48:51]
	s_nop 2
	ds_read_b64_tr_b16 v[48:49], v183 offset:18464
	ds_read_b64_tr_b16 v[184:185], v183 offset:18496
	ds_read_b64_tr_b16 v[188:189], v183 offset:18528
	ds_read_b64_tr_b16 v[50:51], v183 offset:21024
	ds_read_b64_tr_b16 v[186:187], v183 offset:21056
	ds_read_b64_tr_b16 v[190:191], v183 offset:21088
	s_waitcnt lgkmcnt(6)
	v_mfma_f32_16x16x32_bf16 v[76:79], v[60:63], v[160:163], v[76:79]
	v_mfma_f32_16x16x32_bf16 v[72:75], v[60:63], v[164:167], v[68:71]
	s_waitcnt lgkmcnt(2)
	v_mfma_f32_16x16x32_bf16 v[60:63], v[48:51], v[160:163], v[148:151]
	v_mfma_f32_16x16x32_bf16 v[56:59], v[48:51], v[164:167], v[56:59]
	s_waitcnt lgkmcnt(1)
	v_mfma_f32_16x16x32_bf16 v[64:67], v[184:187], v[160:163], v[64:67]
	v_mfma_f32_16x16x32_bf16 v[48:51], v[184:187], v[164:167], v[52:55]
	s_waitcnt lgkmcnt(0)
	v_mfma_f32_16x16x32_bf16 v[68:71], v[188:191], v[160:163], v[152:155]
	v_mfma_f32_16x16x32_bf16 v[52:55], v[188:191], v[164:167], v[156:159]
	s_cbranch_scc1 .LBB0_736
	s_waitcnt vmcnt(2)
	ds_write_b128 v178, v[20:23] offset:23552
	s_waitcnt vmcnt(1)
	ds_write_b128 v180, v[24:27] offset:36864
	s_and_saveexec_b64 s[28:29], s[4:5]
	s_cbranch_execz .LBB0_735
	s_waitcnt vmcnt(0)
	ds_write_b128 v181, v[32:35] offset:23680
